# pool items: the five staging loads issued together with one wait; the eight pool_scale loads of the output stage issued together (were dependent load + full wait per tile)
# speedup vs baseline: 1.0129x; 1.0129x over previous
.LBB0_1228:
	s_or_b64 exec, exec, s[14:15]
	v_mad_u32_u24 v204, v135, s33, v134
.LBB0_1229:
	s_or_b64 exec, exec, s[10:11]
	s_movk_i32 s8, 0x6f0
	v_cmp_gt_i32_e32 vcc, s8, v164
	s_and_saveexec_b64 s[10:11], vcc
	s_cbranch_execz .LBB0_1233
	v_add_u32_e32 v188, 0x200, v164
	v_ashrrev_i32_e32 v135, 4, v188
	v_cmp_lt_i32_e32 vcc, s2, v135
	v_mov_b32_e32 v188, 0
	v_mov_b32_e32 v189, 0
	v_mov_b32_e32 v190, 0
	v_mov_b32_e32 v191, 0
	s_and_saveexec_b64 s[14:15], vcc
	s_cbranch_execz .LBB0_1232
	v_readlane_b32 s8, v253, 31
	s_nop 1
	v_add_u32_e32 v188, s8, v135
	v_mad_i64_i32 v[188:189], s[8:9], v188, s70, v[136:137]
	global_load_dwordx4 v[188:191], v[188:189], off
.LBB0_1232:
	s_or_b64 exec, exec, s[14:15]
	v_mad_u32_u24 v205, v135, s33, v134
.LBB0_1233:
	s_or_b64 exec, exec, s[10:11]
	s_movk_i32 s8, 0x4f0
	v_cmp_gt_i32_e32 vcc, s8, v164
	s_and_saveexec_b64 s[10:11], vcc
	s_cbranch_execz .LBB0_1237
	v_add_u32_e32 v192, 0x400, v164
	v_ashrrev_i32_e32 v135, 4, v192
	v_cmp_lt_i32_e32 vcc, s2, v135
	v_mov_b32_e32 v192, 0
	v_mov_b32_e32 v193, 0
	v_mov_b32_e32 v194, 0
	v_mov_b32_e32 v195, 0
	s_and_saveexec_b64 s[14:15], vcc
	s_cbranch_execz .LBB0_1236
	v_readlane_b32 s8, v253, 31
	s_nop 1
	v_add_u32_e32 v192, s8, v135
	v_mad_i64_i32 v[192:193], s[8:9], v192, s70, v[136:137]
	global_load_dwordx4 v[192:195], v[192:193], off
.LBB0_1236:
	s_or_b64 exec, exec, s[14:15]
	v_mad_u32_u24 v206, v135, s33, v134
.LBB0_1237:
	s_or_b64 exec, exec, s[10:11]
	s_movk_i32 s8, 0x2f0
	v_cmp_gt_i32_e32 vcc, s8, v164
	s_and_saveexec_b64 s[10:11], vcc
	s_cbranch_execz .LBB0_1241
	v_add_u32_e32 v196, 0x600, v164
	v_ashrrev_i32_e32 v135, 4, v196
	v_cmp_lt_i32_e32 vcc, s2, v135
	v_mov_b32_e32 v196, 0
	v_mov_b32_e32 v197, 0
	v_mov_b32_e32 v198, 0
	v_mov_b32_e32 v199, 0
	s_and_saveexec_b64 s[14:15], vcc
	s_cbranch_execz .LBB0_1240
	v_readlane_b32 s8, v253, 31
	s_nop 1
	v_add_u32_e32 v196, s8, v135
	v_mad_i64_i32 v[196:197], s[8:9], v196, s70, v[136:137]
	global_load_dwordx4 v[196:199], v[196:197], off
.LBB0_1240:
	s_or_b64 exec, exec, s[14:15]
	v_mad_u32_u24 v207, v135, s33, v134
.LBB0_1241:
	s_or_b64 exec, exec, s[10:11]
	s_movk_i32 s8, 0xf0
	v_cmp_gt_i32_e32 vcc, s8, v164
	s_and_saveexec_b64 s[10:11], vcc
	s_cbranch_execz .LBB0_1245
	v_add_u32_e32 v200, 0x800, v164
	v_ashrrev_i32_e32 v135, 4, v200
	v_cmp_lt_i32_e32 vcc, s2, v135
	v_mov_b32_e32 v200, 0
	v_mov_b32_e32 v201, 0
	v_mov_b32_e32 v202, 0
	v_mov_b32_e32 v203, 0
	s_and_saveexec_b64 s[14:15], vcc
	s_cbranch_execz .LBB0_1244
	v_readlane_b32 s2, v253, 31
	s_nop 1
	v_add_u32_e32 v200, s2, v135
	v_mad_i64_i32 v[200:201], s[8:9], v200, s70, v[136:137]
	global_load_dwordx4 v[200:203], v[200:201], off
.LBB0_1244:
	s_or_b64 exec, exec, s[14:15]
	v_mad_u32_u24 v208, v135, s33, v134
.LBB0_1245:
	s_or_b64 exec, exec, s[10:11]
	s_waitcnt vmcnt(0)
	s_movk_i32 s8, 0x8f0
	v_cmp_gt_i32_e32 vcc, s8, v164
	s_and_saveexec_b64 s[10:11], vcc
	ds_write_b128 v204, v[130:133]
	s_or_b64 exec, exec, s[10:11]
	s_movk_i32 s8, 0x6f0
	v_cmp_gt_i32_e32 vcc, s8, v164
	s_and_saveexec_b64 s[10:11], vcc
	ds_write_b128 v205, v[188:191]
	s_or_b64 exec, exec, s[10:11]
	s_movk_i32 s8, 0x4f0
	v_cmp_gt_i32_e32 vcc, s8, v164
	s_and_saveexec_b64 s[10:11], vcc
	ds_write_b128 v206, v[192:195]
	s_or_b64 exec, exec, s[10:11]
	s_movk_i32 s8, 0x2f0
	v_cmp_gt_i32_e32 vcc, s8, v164
	s_and_saveexec_b64 s[10:11], vcc
	ds_write_b128 v207, v[196:199]
	s_or_b64 exec, exec, s[10:11]
	s_movk_i32 s8, 0xf0
	v_cmp_gt_i32_e32 vcc, s8, v164
	s_and_saveexec_b64 s[10:11], vcc
	ds_write_b128 v208, v[200:203]
	s_or_b64 exec, exec, s[10:11]
	v_ashrrev_i32_e32 v168, 2, v164
	v_lshlrev_b32_e32 v130, 6, v164
	v_mul_lo_u32 v166, v168, s33
	v_and_b32_e32 v167, 0xc0, v130
	v_readlane_b32 s2, v254, 56
	v_mov_b32_e32 v130, 0
	v_mov_b32_e32 v131, v130
	v_add3_u32 v169, v166, v167, s2
	v_readlane_b32 s2, v253, 19
	v_mov_b32_e32 v160, v130
	v_mov_b32_e32 v161, v130
	v_mov_b32_e32 v158, v130
	v_mov_b32_e32 v159, v130
	v_mov_b32_e32 v156, v130
	v_mov_b32_e32 v157, v130
	v_mov_b32_e32 v154, v130
	v_mov_b32_e32 v155, v130
	v_mov_b32_e32 v152, v130
	v_mov_b32_e32 v153, v130
	v_mov_b32_e32 v150, v130
	v_mov_b32_e32 v151, v130
	v_mov_b32_e32 v148, v130
	v_mov_b32_e32 v149, v130
	v_mov_b32_e32 v146, v130
	v_mov_b32_e32 v147, v130
	v_mov_b32_e32 v144, v130
	v_mov_b32_e32 v145, v130
	v_mov_b32_e32 v142, v130
	v_mov_b32_e32 v143, v130
	v_mov_b32_e32 v140, v130
	v_mov_b32_e32 v141, v130
	v_mov_b32_e32 v138, v130
	v_mov_b32_e32 v139, v130
	v_mov_b32_e32 v136, v130
	v_mov_b32_e32 v137, v130
	v_mov_b32_e32 v134, v130
	v_mov_b32_e32 v135, v130
	v_mov_b32_e32 v132, v130
	v_mov_b32_e32 v133, v130
	s_waitcnt lgkmcnt(0)
	s_barrier
.LBB0_1246:
	ds_read_b128 v[170:173], v169
	ds_read_b128 v[174:177], v169 offset:16
	ds_read_b128 v[178:181], v169 offset:32
	ds_read_b128 v[182:185], v169 offset:48
	s_add_i32 s2, s2, -1
	s_waitcnt lgkmcnt(3)
	v_lshlrev_b32_e32 v186, 16, v170
	v_and_b32_e32 v187, 0xffff0000, v170
	v_lshlrev_b32_e32 v170, 16, v171
	v_and_b32_e32 v171, 0xffff0000, v171
	v_pk_add_f32 v[158:159], v[158:159], v[170:171]
	v_lshlrev_b32_e32 v170, 16, v172
	v_and_b32_e32 v171, 0xffff0000, v172
	v_pk_add_f32 v[156:157], v[156:157], v[170:171]
	v_lshlrev_b32_e32 v170, 16, v173
	v_and_b32_e32 v171, 0xffff0000, v173
	v_pk_add_f32 v[154:155], v[154:155], v[170:171]
	s_waitcnt lgkmcnt(2)
	v_lshlrev_b32_e32 v170, 16, v174
	v_and_b32_e32 v171, 0xffff0000, v174
	v_pk_add_f32 v[152:153], v[152:153], v[170:171]
	v_lshlrev_b32_e32 v170, 16, v175
	v_and_b32_e32 v171, 0xffff0000, v175
	v_pk_add_f32 v[150:151], v[150:151], v[170:171]
	v_lshlrev_b32_e32 v170, 16, v176
	v_and_b32_e32 v171, 0xffff0000, v176
	v_pk_add_f32 v[148:149], v[148:149], v[170:171]
	v_lshlrev_b32_e32 v170, 16, v177
	v_and_b32_e32 v171, 0xffff0000, v177
	v_pk_add_f32 v[146:147], v[146:147], v[170:171]
	s_waitcnt lgkmcnt(1)
	v_lshlrev_b32_e32 v170, 16, v178
	v_and_b32_e32 v171, 0xffff0000, v178
	v_pk_add_f32 v[144:145], v[144:145], v[170:171]
	v_lshlrev_b32_e32 v170, 16, v179
	v_and_b32_e32 v171, 0xffff0000, v179
	v_pk_add_f32 v[142:143], v[142:143], v[170:171]
	v_lshlrev_b32_e32 v170, 16, v180
	v_and_b32_e32 v171, 0xffff0000, v180
	v_pk_add_f32 v[140:141], v[140:141], v[170:171]
	v_lshlrev_b32_e32 v170, 16, v181
	v_and_b32_e32 v171, 0xffff0000, v181
	v_pk_add_f32 v[138:139], v[138:139], v[170:171]
	s_waitcnt lgkmcnt(0)
	v_lshlrev_b32_e32 v170, 16, v182
	v_and_b32_e32 v171, 0xffff0000, v182
	v_pk_add_f32 v[136:137], v[136:137], v[170:171]
	v_lshlrev_b32_e32 v170, 16, v183
	v_and_b32_e32 v171, 0xffff0000, v183
	v_pk_add_f32 v[134:135], v[134:135], v[170:171]
	v_lshlrev_b32_e32 v170, 16, v184
	v_and_b32_e32 v171, 0xffff0000, v184
	v_pk_add_f32 v[132:133], v[132:133], v[170:171]
	v_lshlrev_b32_e32 v170, 16, v185
	v_and_b32_e32 v171, 0xffff0000, v185
	v_pk_add_f32 v[160:161], v[160:161], v[186:187]
	v_pk_add_f32 v[130:131], v[130:131], v[170:171]
	v_add_u32_e32 v169, 0xfffffef0, v169
	s_cmp_lg_u32 s2, 0
	s_cbranch_scc1 .LBB0_1246
	v_readlane_b32 s2, v253, 26
	v_add3_u32 v182, 0, v166, v167
	v_readlane_b32 s48, v251, 4
	v_add_u32_e32 v168, s2, v168
	v_readlane_b32 s2, v253, 19
	v_readlane_b32 s50, v251, 6
	v_readlane_b32 s51, v251, 7
	v_min_i32_e32 v168, s2, v168
	v_cvt_f32_i32_e32 v170, v168
	s_mov_b64 s[74:75], s[50:51]
	s_add_u32 s2, s74, s12
	s_addc_u32 s14, s75, s13
	v_div_scale_f32 v168, s[8:9], v170, v170, 1.0
	v_rcp_f32_e32 v169, v168
	v_div_scale_f32 v171, vcc, 1.0, v170, 1.0
	s_ashr_i32 s8, s17, 2
	v_fma_f32 v172, -v168, v169, 1.0
	v_fmac_f32_e32 v169, v172, v169
	v_mul_f32_e32 v172, v171, v169
	v_fma_f32 v173, -v168, v172, v171
	v_fmac_f32_e32 v172, v173, v169
	v_fma_f32 v168, -v168, v172, v171
	v_div_fmas_f32 v171, v168, v169, v172
	ds_read_b128 v[166:169], v182 offset:4080
	v_div_fixup_f32 v183, v171, v170, 1.0
	ds_read_b128 v[170:173], v182 offset:4096
	ds_read_b128 v[174:177], v182 offset:4112
	ds_read_b128 v[178:181], v182 offset:4128
	s_mov_b64 s[10:11], 0x11101000
	v_readlane_b32 s49, v251, 5
	s_waitcnt lgkmcnt(3)
	v_lshlrev_b32_e32 v184, 16, v166
	v_fma_f32 v160, v183, v160, -v184
	v_and_b32_e32 v166, 0xffff0000, v166
	v_fma_f32 v161, v183, v161, -v166
	v_cvt_pk_bf16_f32 v166, v160, v161
	v_lshlrev_b32_e32 v160, 16, v167
	v_fma_f32 v158, v183, v158, -v160
	v_and_b32_e32 v160, 0xffff0000, v167
	v_fma_f32 v159, v183, v159, -v160
	v_cvt_pk_bf16_f32 v167, v158, v159
	v_lshlrev_b32_e32 v158, 16, v168
	v_fma_f32 v156, v183, v156, -v158
	v_and_b32_e32 v158, 0xffff0000, v168
	v_fma_f32 v157, v183, v157, -v158
	v_cvt_pk_bf16_f32 v168, v156, v157
	v_lshlrev_b32_e32 v156, 16, v169
	v_fma_f32 v154, v183, v154, -v156
	v_and_b32_e32 v156, 0xffff0000, v169
	v_fma_f32 v155, v183, v155, -v156
	v_cvt_pk_bf16_f32 v169, v154, v155
	s_waitcnt lgkmcnt(2)
	v_lshlrev_b32_e32 v154, 16, v170
	v_fma_f32 v152, v183, v152, -v154
	v_and_b32_e32 v154, 0xffff0000, v170
	v_fma_f32 v153, v183, v153, -v154
	v_cvt_pk_bf16_f32 v152, v152, v153
	v_lshlrev_b32_e32 v153, 16, v171
	v_fma_f32 v150, v183, v150, -v153
	v_and_b32_e32 v153, 0xffff0000, v171
	v_fma_f32 v151, v183, v151, -v153
	v_cvt_pk_bf16_f32 v153, v150, v151
	v_lshlrev_b32_e32 v150, 16, v172
	v_fma_f32 v148, v183, v148, -v150
	v_and_b32_e32 v150, 0xffff0000, v172
	v_fma_f32 v149, v183, v149, -v150
	v_cvt_pk_bf16_f32 v154, v148, v149
	v_lshlrev_b32_e32 v148, 16, v173
	v_fma_f32 v146, v183, v146, -v148
	v_and_b32_e32 v148, 0xffff0000, v173
	v_fma_f32 v147, v183, v147, -v148
	v_cvt_pk_bf16_f32 v155, v146, v147
	s_waitcnt lgkmcnt(1)
	v_lshlrev_b32_e32 v146, 16, v174
	v_fma_f32 v144, v183, v144, -v146
	v_and_b32_e32 v146, 0xffff0000, v174
	v_fma_f32 v145, v183, v145, -v146
	v_cvt_pk_bf16_f32 v144, v144, v145
	v_lshlrev_b32_e32 v145, 16, v175
	v_fma_f32 v142, v183, v142, -v145
	v_and_b32_e32 v145, 0xffff0000, v175
	v_fma_f32 v143, v183, v143, -v145
	v_cvt_pk_bf16_f32 v145, v142, v143
	v_lshlrev_b32_e32 v142, 16, v176
	v_fma_f32 v140, v183, v140, -v142
	v_and_b32_e32 v142, 0xffff0000, v176
	v_fma_f32 v141, v183, v141, -v142
	v_cvt_pk_bf16_f32 v146, v140, v141
	v_lshlrev_b32_e32 v140, 16, v177
	v_fma_f32 v138, v183, v138, -v140
	v_and_b32_e32 v140, 0xffff0000, v177
	v_fma_f32 v139, v183, v139, -v140
	v_cvt_pk_bf16_f32 v147, v138, v139
	s_waitcnt lgkmcnt(0)
	v_lshlrev_b32_e32 v138, 16, v178
	v_fma_f32 v136, v183, v136, -v138
	v_and_b32_e32 v138, 0xffff0000, v178
	v_fma_f32 v137, v183, v137, -v138
	v_cvt_pk_bf16_f32 v136, v136, v137
	v_lshlrev_b32_e32 v137, 16, v179
	v_fma_f32 v134, v183, v134, -v137
	v_and_b32_e32 v137, 0xffff0000, v179
	v_fma_f32 v135, v183, v135, -v137
	v_cvt_pk_bf16_f32 v137, v134, v135
	v_lshlrev_b32_e32 v134, 16, v180
	v_fma_f32 v132, v183, v132, -v134
	v_and_b32_e32 v134, 0xffff0000, v180
	v_fma_f32 v133, v183, v133, -v134
	v_cvt_pk_bf16_f32 v138, v132, v133
	v_lshlrev_b32_e32 v132, 16, v181
	v_fma_f32 v130, v183, v130, -v132
	v_and_b32_e32 v132, 0xffff0000, v181
	v_fma_f32 v131, v183, v131, -v132
	v_and_or_b32 v142, s8, -16, v165
	v_cvt_pk_bf16_f32 v139, v130, v131
	v_mul_lo_u32 v130, v142, s33
	v_and_b32_e32 v131, 48, v164
	v_add3_u32 v143, 0, v130, v131
	ds_write_b128 v182, v[166:169] offset:40960
	ds_write_b128 v182, v[152:155] offset:40976
	ds_write_b128 v182, v[144:147] offset:40992
	ds_write_b128 v182, v[136:139] offset:41008
	s_waitcnt lgkmcnt(0)
	s_barrier
	ds_read_b128 v[134:137], v143 offset:40960
	ds_read_b128 v[130:133], v143 offset:41024
	s_waitcnt vmcnt(31) lgkmcnt(1)
	v_mfma_f32_16x16x32_bf16 v[122:125], v[122:125], v[134:137], 0
	v_readlane_b32 s8, v253, 30
	v_mov_b32_e32 v164, v218
	v_readlane_b32 s52, v251, 8
	s_waitcnt vmcnt(30) lgkmcnt(0)
	v_mfma_f32_16x16x32_bf16 v[138:141], v[118:121], v[130:133], v[122:125]
	s_nop 2
	ds_read_b128 v[122:125], v143 offset:41088
	ds_read_b128 v[118:121], v143 offset:41152
	v_readlane_b32 s53, v251, 9
	v_readlane_b32 s54, v251, 10
	s_waitcnt vmcnt(29) lgkmcnt(1)
	v_mfma_f32_16x16x32_bf16 v[114:117], v[114:117], v[122:125], v[138:141]
	v_readlane_b32 s55, v251, 11
	v_readlane_b32 s56, v251, 12
	v_readlane_b32 s57, v251, 13
	s_waitcnt vmcnt(28) lgkmcnt(0)
	v_mfma_f32_16x16x32_bf16 v[110:113], v[110:113], v[118:121], v[114:117]
	v_readlane_b32 s58, v251, 14
	v_readlane_b32 s59, v251, 15
	v_readlane_b32 s60, v251, 16
	s_waitcnt vmcnt(1)
	v_mfma_f32_16x16x32_bf16 v[114:117], v[126:129], v[134:137], 0
	v_readlane_b32 s61, v251, 17
	v_readlane_b32 s62, v251, 18
	v_readlane_b32 s63, v251, 19
	v_mfma_f32_16x16x32_bf16 v[106:109], v[106:109], v[130:133], v[114:117]
	v_mfma_f32_16x16x32_bf16 v[98:101], v[98:101], v[134:137], 0
	s_nop 2
	v_add_u32_e32 v114, s8, v142
	v_mfma_f32_16x16x32_bf16 v[102:105], v[102:105], v[122:125], v[106:109]
	s_nop 2
	v_mov_b64_e32 v[106:107], s[24:25]
	v_mad_i64_i32 v[106:107], s[8:9], v114, s70, v[106:107]
	v_mfma_f32_16x16x32_bf16 v[86:89], v[86:89], v[134:137], 0
	v_readlane_b32 s8, v253, 21
	s_lshl_b32 s28, s8, 1
	v_lshl_add_u64 v[106:107], v[106:107], 0, s[28:29]
	v_mfma_f32_16x16x32_bf16 v[96:99], v[94:97], v[130:133], v[98:101]
	v_lshlrev_b32_e32 v108, 3, v163
	v_mov_b32_e32 v109, v33
	s_mov_b32 s9, 0x11101000
	v_lshl_add_u64 v[100:101], v[106:107], 0, v[108:109]
	v_mfma_f32_16x16x32_bf16 v[84:87], v[82:85], v[130:133], v[86:89]
	s_lshl_b32 s8, s8, 2
	v_lshl_add_u64 v[94:95], v[100:101], 0, s[10:11]
	s_add_u32 s10, s2, s8
	v_mfma_f32_16x16x32_bf16 v[90:93], v[90:93], v[122:125], v[96:99]
	s_addc_u32 s11, s14, 0
	v_readlane_b32 s8, v253, 28
	s_or_b32 s8, s8, s16
	v_add_co_u32_e32 v96, vcc, s9, v100
	v_mfma_f32_16x16x32_bf16 v[78:81], v[78:81], v[122:125], v[84:87]
	s_nop 0
	v_addc_co_u32_e32 v97, vcc, 0, v101, vcc
	global_load_dwordx2 v[98:99], v[94:95], off offset:32
	global_load_dwordx2 v[100:101], v[94:95], off offset:64
	global_load_dwordx2 v[106:107], v[94:95], off offset:96
	global_load_dwordx2 v[108:109], v[94:95], off offset:128
	global_load_dwordx2 v[88:89], v[96:97], off
	global_load_dwordx2 v[114:115], v[94:95], off offset:160
	global_load_dwordx2 v[116:117], v[94:95], off offset:192
	global_load_dwordx2 v[82:83], v[94:95], off offset:224
	global_load_dwordx4 v[84:87], v32, s[10:11]
	global_load_dwordx4 v[188:191], v32, s[10:11] offset:64
	global_load_dwordx4 v[192:195], v32, s[10:11] offset:128
	global_load_dwordx4 v[196:199], v32, s[10:11] offset:192
	global_load_dwordx4 v[200:203], v32, s[10:11] offset:256
	global_load_dwordx4 v[210:213], v32, s[10:11] offset:320
	global_load_dwordx4 v[214:217], v32, s[10:11] offset:384
	global_load_dwordx4 v[228:231], v32, s[10:11] offset:448
	v_mfma_f32_16x16x32_bf16 v[74:77], v[74:77], v[134:137], 0
	v_readlane_b32 s9, v252, 29
	s_add_u32 s8, s9, s8
	v_readlane_b32 s9, v252, 30
	v_mfma_f32_16x16x32_bf16 v[62:65], v[62:65], v[134:137], 0
	s_addc_u32 s9, s9, 0
	v_mfma_f32_16x16x32_bf16 v[70:73], v[70:73], v[130:133], v[74:77]
	v_mfma_f32_16x16x32_bf16 v[58:61], v[58:61], v[130:133], v[62:65]
	s_waitcnt vmcnt(4)
	s_nop 0
	v_lshlrev_b32_e32 v75, 16, v88
	v_mfma_f32_16x16x32_bf16 v[66:69], v[66:69], v[122:125], v[70:73]
	s_nop 0
	v_and_b32_e32 v64, 0xffff0000, v89
	s_waitcnt vmcnt(0)
	v_mul_f32_e32 v74, v110, v84
	v_mul_f32_e32 v70, v111, v85
	v_and_b32_e32 v71, 0xffff0000, v88
	v_mul_f32_e32 v70, v70, v71
	v_mul_f32_e32 v71, v112, v86
	v_lshlrev_b32_e32 v72, 16, v89
	v_mul_f32_e32 v63, v113, v87
	v_mul_f32_e32 v74, v74, v75
	v_cvt_pk_bf16_f32 v70, v74, v70
	v_mul_f32_e32 v62, v71, v72
	v_mfma_f32_16x16x32_bf16 v[54:57], v[54:57], v[122:125], v[58:61]
	s_nop 2
	v_mul_f32_e32 v58, v63, v64
	v_cvt_pk_bf16_f32 v71, v62, v58
	global_store_dwordx2 v[96:97], v[70:71], off
	v_mov_b64_e32 v[58:59], v[188:189]
	v_mov_b64_e32 v[60:61], v[190:191]
	v_mfma_f32_16x16x32_bf16 v[50:53], v[50:53], v[134:137], 0
	v_lshlrev_b32_e32 v62, 16, v98
	v_mfma_f32_16x16x32_bf16 v[28:31], v[28:31], v[118:121], v[102:105]
	v_mfma_f32_16x16x32_bf16 v[46:49], v[46:49], v[130:133], v[50:53]
	v_mfma_f32_16x16x32_bf16 v[42:45], v[42:45], v[122:125], v[46:49]
	s_nop 4
	v_mul_f32_e32 v28, v28, v58
	v_mul_f32_e32 v29, v29, v59
	v_and_b32_e32 v58, 0xffff0000, v98
	v_mul_f32_e32 v28, v28, v62
	v_mul_f32_e32 v29, v29, v58
	v_cvt_pk_bf16_f32 v50, v28, v29
	v_mul_f32_e32 v28, v30, v60
	v_lshlrev_b32_e32 v29, 16, v99
	v_mul_f32_e32 v46, v28, v29
	v_mul_f32_e32 v47, v31, v61
	v_mfma_f32_16x16x32_bf16 v[28:31], v[38:41], v[134:137], 0
	v_and_b32_e32 v48, 0xffff0000, v99
	v_mul_f32_e32 v38, v47, v48
	v_cvt_pk_bf16_f32 v51, v46, v38
	global_store_dwordx2 v[94:95], v[50:51], off offset:32
	v_mfma_f32_16x16x32_bf16 v[28:31], v[34:37], v[130:133], v[28:31]
	v_mov_b64_e32 v[34:35], v[192:193]
	v_mov_b64_e32 v[36:37], v[194:195]
	v_lshlrev_b32_e32 v38, 16, v100
	v_and_b32_e32 v39, 0xffff0000, v100
	v_mfma_f32_16x16x32_bf16 v[24:27], v[24:27], v[118:121], v[90:93]
	v_lshlrev_b32_e32 v40, 16, v101
	v_and_b32_e32 v41, 0xffff0000, v101
	v_mov_b32_e32 v131, v33
	v_mfma_f32_16x16x32_bf16 v[16:19], v[16:19], v[118:121], v[78:81]
	v_mfma_f32_16x16x32_bf16 v[20:23], v[20:23], v[118:121], v[66:69]
	s_nop 1
	v_mul_f32_e32 v24, v24, v34
	v_mul_f32_e32 v25, v25, v35
	v_mul_f32_e32 v26, v26, v36
	v_mul_f32_e32 v27, v27, v37
	v_mul_f32_e32 v24, v24, v38
	v_mul_f32_e32 v25, v25, v39
	v_mul_f32_e32 v26, v26, v40
	v_mul_f32_e32 v27, v27, v41
	v_cvt_pk_bf16_f32 v24, v24, v25
	v_cvt_pk_bf16_f32 v25, v26, v27
	global_store_dwordx2 v[94:95], v[24:25], off offset:64
	v_mov_b64_e32 v[24:25], v[196:197]
	v_mov_b64_e32 v[26:27], v[198:199]
	v_lshlrev_b32_e32 v34, 16, v106
	v_and_b32_e32 v35, 0xffff0000, v106
	v_lshlrev_b32_e32 v36, 16, v107
	v_and_b32_e32 v37, 0xffff0000, v107
	v_mfma_f32_16x16x32_bf16 v[12:15], v[12:15], v[118:121], v[54:57]
	v_mul_f32_e32 v16, v16, v24
	v_mul_f32_e32 v17, v17, v25
	v_mul_f32_e32 v18, v18, v26
	v_mul_f32_e32 v19, v19, v27
	v_mul_f32_e32 v16, v16, v34
	v_mul_f32_e32 v17, v17, v35
	v_mul_f32_e32 v18, v18, v36
	v_mul_f32_e32 v19, v19, v37
	v_cvt_pk_bf16_f32 v16, v16, v17
	v_cvt_pk_bf16_f32 v17, v18, v19
	global_store_dwordx2 v[94:95], v[16:17], off offset:96
	v_mov_b64_e32 v[16:17], v[200:201]
	v_mov_b64_e32 v[18:19], v[202:203]
	v_lshlrev_b32_e32 v24, 16, v108
	v_and_b32_e32 v25, 0xffff0000, v108
	v_lshlrev_b32_e32 v26, 16, v109
	v_and_b32_e32 v27, 0xffff0000, v109
	v_mfma_f32_16x16x32_bf16 v[8:11], v[8:11], v[118:121], v[42:45]
	v_mul_f32_e32 v16, v20, v16
	v_mul_f32_e32 v17, v21, v17
	v_mul_f32_e32 v18, v22, v18
	v_mul_f32_e32 v19, v23, v19
	v_mul_f32_e32 v16, v16, v24
	v_mul_f32_e32 v17, v17, v25
	v_mul_f32_e32 v18, v18, v26
	v_mul_f32_e32 v19, v19, v27
	v_cvt_pk_bf16_f32 v16, v16, v17
	v_cvt_pk_bf16_f32 v17, v18, v19
	global_store_dwordx2 v[94:95], v[16:17], off offset:128
	v_mov_b64_e32 v[16:17], v[210:211]
	v_mov_b64_e32 v[18:19], v[212:213]
	v_lshlrev_b32_e32 v20, 16, v114
	v_and_b32_e32 v21, 0xffff0000, v114
	v_lshlrev_b32_e32 v22, 16, v115
	v_and_b32_e32 v23, 0xffff0000, v115
	v_mfma_f32_16x16x32_bf16 v[4:7], v[4:7], v[122:125], v[28:31]
	v_mul_f32_e32 v12, v12, v16
	v_mul_f32_e32 v13, v13, v17
	v_mul_f32_e32 v14, v14, v18
	v_mul_f32_e32 v15, v15, v19
	v_mul_f32_e32 v12, v12, v20
	v_mul_f32_e32 v13, v13, v21
	v_mul_f32_e32 v14, v14, v22
	v_mul_f32_e32 v15, v15, v23
	v_cvt_pk_bf16_f32 v12, v12, v13
	v_cvt_pk_bf16_f32 v13, v14, v15
	global_store_dwordx2 v[94:95], v[12:13], off offset:160
	v_mov_b64_e32 v[12:13], v[214:215]
	v_mov_b64_e32 v[14:15], v[216:217]
	v_lshlrev_b32_e32 v16, 16, v116
	v_and_b32_e32 v17, 0xffff0000, v116
	v_lshlrev_b32_e32 v18, 16, v117
	v_and_b32_e32 v19, 0xffff0000, v117
	v_mfma_f32_16x16x32_bf16 v[0:3], v[0:3], v[118:121], v[4:7]
	v_mul_f32_e32 v8, v8, v12
	v_mul_f32_e32 v9, v9, v13
	v_mul_f32_e32 v10, v10, v14
	v_mul_f32_e32 v11, v11, v15
	v_mul_f32_e32 v8, v8, v16
	v_mul_f32_e32 v9, v9, v17
	v_mul_f32_e32 v10, v10, v18
	v_mul_f32_e32 v11, v11, v19
	v_cvt_pk_bf16_f32 v8, v8, v9
	v_cvt_pk_bf16_f32 v9, v10, v11
	global_store_dwordx2 v[94:95], v[8:9], off offset:192
	v_mov_b64_e32 v[8:9], v[228:229]
	v_mov_b64_e32 v[10:11], v[230:231]
	v_lshlrev_b32_e32 v4, 16, v82
	v_and_b32_e32 v5, 0xffff0000, v82
	v_lshlrev_b32_e32 v6, 16, v83
	v_and_b32_e32 v7, 0xffff0000, v83
	v_mul_f32_e32 v0, v0, v8
	v_mul_f32_e32 v1, v1, v9
	v_mul_f32_e32 v2, v2, v10
	v_mul_f32_e32 v3, v3, v11
	v_mul_f32_e32 v0, v0, v4
	v_mul_f32_e32 v1, v1, v5
	v_mul_f32_e32 v2, v2, v6
	v_mul_f32_e32 v3, v3, v7
	v_cvt_pk_bf16_f32 v0, v0, v1
	v_cvt_pk_bf16_f32 v1, v2, v3
	global_store_dwordx2 v[94:95], v[0:1], off offset:224
	s_barrier
	s_nop 0
	v_and_b32_e32 v165, 15, v164
	v_bfe_u32 v163, v164, 4, 2
	v_lshlrev_b32_e32 v32, 8, v165
	v_lshl_add_u64 v[0:1], s[8:9], 0, v[32:33]
	v_lshlrev_b32_e32 v32, 4, v163
	v_lshl_add_u64 v[0:1], v[0:1], 0, v[32:33]
	s_movk_i32 s8, 0x1000
	v_add_co_u32_e32 v2, vcc, s8, v0
	s_movk_i32 s8, 0x3000
	s_nop 0
	v_addc_co_u32_e32 v3, vcc, 0, v1, vcc
	v_add_co_u32_e32 v12, vcc, s1, v0
	global_load_dwordx4 v[114:117], v[0:1], off
	global_load_dwordx4 v[110:113], v[0:1], off offset:64
	global_load_dwordx4 v[106:109], v[0:1], off offset:128
	global_load_dwordx4 v[102:105], v[0:1], off offset:192
	v_addc_co_u32_e32 v13, vcc, 0, v1, vcc
	v_add_co_u32_e32 v4, vcc, s8, v0
	s_movk_i32 s8, 0x4000
	s_nop 0
	v_addc_co_u32_e32 v5, vcc, 0, v1, vcc
	v_add_co_u32_e32 v6, vcc, s8, v0
	s_movk_i32 s8, 0x5000
	s_nop 0
	v_addc_co_u32_e32 v7, vcc, 0, v1, vcc
	global_load_dwordx4 v[122:125], v[2:3], off offset:64
	global_load_dwordx4 v[118:121], v[2:3], off offset:128
	global_load_dwordx4 v[98:101], v[12:13], off
	global_load_dwordx4 v[94:97], v[12:13], off offset:64
	global_load_dwordx4 v[90:93], v[12:13], off offset:128
	global_load_dwordx4 v[20:23], v[12:13], off offset:192
	global_load_dwordx4 v[38:41], v[2:3], off offset:192
	global_load_dwordx4 v[78:81], v[4:5], off offset:64
	global_load_dwordx4 v[74:77], v[4:5], off offset:128
	global_load_dwordx4 v[16:19], v[4:5], off offset:192
	global_load_dwordx4 v[82:85], v[6:7], off offset:-4096
	global_load_dwordx4 v[70:73], v[6:7], off
	global_load_dwordx4 v[66:69], v[6:7], off offset:64
	global_load_dwordx4 v[58:61], v[6:7], off offset:128
	v_add_co_u32_e32 v8, vcc, s8, v0
	s_movk_i32 s8, 0x6000
	s_nop 0
	v_addc_co_u32_e32 v9, vcc, 0, v1, vcc
	v_add_co_u32_e32 v2, vcc, s8, v0
	global_load_dwordx4 v[62:65], v[8:9], off offset:64
	global_load_dwordx4 v[50:53], v[8:9], off offset:128
	v_addc_co_u32_e32 v3, vcc, 0, v1, vcc
	v_add_co_u32_e32 v14, vcc, 0x7000, v0
	global_load_dwordx4 v[34:37], v[6:7], off offset:192
	global_load_dwordx4 v[86:89], v[2:3], off offset:-4096
	global_load_dwordx4 v[54:57], v[2:3], off
	global_load_dwordx4 v[46:49], v[2:3], off offset:64
	global_load_dwordx4 v[42:45], v[2:3], off offset:128
	global_load_dwordx4 v[24:27], v[2:3], off offset:192
	v_addc_co_u32_e32 v15, vcc, 0, v1, vcc
	global_load_dwordx4 v[28:31], v[8:9], off offset:192
	s_nop 0
	global_load_dwordx4 v[8:11], v[14:15], off
	global_load_dwordx4 v[4:7], v[14:15], off offset:64
	global_load_dwordx4 v[0:3], v[14:15], off offset:128
	global_load_dwordx4 v[126:129], v[12:13], off offset:-4096
	s_nop 0
	global_load_dwordx4 v[12:15], v[14:15], off offset:192
	v_readlane_b32 s8, v253, 35
	v_lshlrev_b32_e32 v130, 4, v165
	v_readlane_b32 s9, v253, 36
	v_readfirstlane_b32 s15, v164
	v_add_u32_e32 v134, 0, v130
	v_lshl_add_u64 v[136:137], s[8:9], 0, v[130:131]
	s_movk_i32 s8, 0x8f0
	v_cmp_gt_i32_e32 vcc, s8, v164
	s_and_saveexec_b64 s[10:11], vcc
	v_readlane_b32 s86, v254, 59
	v_readlane_b32 s84, v254, 61
	v_readlane_b32 s87, v254, 60
	v_readlane_b32 s85, v254, 62
	s_cbranch_execz .LBB0_1251
	v_ashrrev_i32_e32 v135, 4, v164
	v_readlane_b32 s8, v253, 38
	v_mov_b32_e32 v130, 0
	v_mov_b32_e32 v131, 0
	v_cmp_lt_i32_e32 vcc, s8, v135
	v_mov_b32_e32 v132, 0
	v_mov_b32_e32 v133, 0
	s_and_saveexec_b64 s[12:13], vcc
	s_cbranch_execz .LBB0_1250
	v_readlane_b32 s8, v253, 37
	s_nop 1
	v_add_u32_e32 v130, s8, v135
	v_mad_i64_i32 v[130:131], s[8:9], v130, s70, v[136:137]
	global_load_dwordx4 v[130:133], v[130:131], off
.LBB0_1250:
	s_or_b64 exec, exec, s[12:13]
	v_mad_u32_u24 v204, v135, s33, v134
.LBB0_1251:
	s_or_b64 exec, exec, s[10:11]
	s_movk_i32 s8, 0x6f0
	v_cmp_gt_i32_e32 vcc, s8, v164
	s_and_saveexec_b64 s[10:11], vcc
	s_cbranch_execz .LBB0_1255
	v_add_u32_e32 v188, 0x200, v164
	v_ashrrev_i32_e32 v135, 4, v188
	v_readlane_b32 s8, v253, 38
	v_mov_b32_e32 v188, 0
	v_mov_b32_e32 v189, 0
	v_cmp_lt_i32_e32 vcc, s8, v135
	v_mov_b32_e32 v190, 0
	v_mov_b32_e32 v191, 0
	s_and_saveexec_b64 s[12:13], vcc
	s_cbranch_execz .LBB0_1254
	v_readlane_b32 s8, v253, 37
	s_nop 1
	v_add_u32_e32 v188, s8, v135
	v_mad_i64_i32 v[188:189], s[8:9], v188, s70, v[136:137]
	global_load_dwordx4 v[188:191], v[188:189], off
.LBB0_1254:
	s_or_b64 exec, exec, s[12:13]
	v_mad_u32_u24 v205, v135, s33, v134
.LBB0_1255:
	s_or_b64 exec, exec, s[10:11]
	s_movk_i32 s8, 0x4f0
	v_cmp_gt_i32_e32 vcc, s8, v164
	s_and_saveexec_b64 s[10:11], vcc
	s_cbranch_execz .LBB0_1259
	v_add_u32_e32 v192, 0x400, v164
	v_ashrrev_i32_e32 v135, 4, v192
	v_readlane_b32 s8, v253, 38
	v_mov_b32_e32 v192, 0
	v_mov_b32_e32 v193, 0
	v_cmp_lt_i32_e32 vcc, s8, v135
	v_mov_b32_e32 v194, 0
	v_mov_b32_e32 v195, 0
	s_and_saveexec_b64 s[12:13], vcc
	s_cbranch_execz .LBB0_1258
	v_readlane_b32 s8, v253, 37
	s_nop 1
	v_add_u32_e32 v192, s8, v135
	v_mad_i64_i32 v[192:193], s[8:9], v192, s70, v[136:137]
	global_load_dwordx4 v[192:195], v[192:193], off
.LBB0_1258:
	s_or_b64 exec, exec, s[12:13]
	v_mad_u32_u24 v206, v135, s33, v134
.LBB0_1259:
	s_or_b64 exec, exec, s[10:11]
	s_movk_i32 s8, 0x2f0
	v_cmp_gt_i32_e32 vcc, s8, v164
	s_and_saveexec_b64 s[10:11], vcc
	s_cbranch_execz .LBB0_1263
	v_add_u32_e32 v196, 0x600, v164
	v_ashrrev_i32_e32 v135, 4, v196
	v_readlane_b32 s8, v253, 38
	v_mov_b32_e32 v196, 0
	v_mov_b32_e32 v197, 0
	v_cmp_lt_i32_e32 vcc, s8, v135
	v_mov_b32_e32 v198, 0
	v_mov_b32_e32 v199, 0
	s_and_saveexec_b64 s[12:13], vcc
	s_cbranch_execz .LBB0_1262
	v_readlane_b32 s8, v253, 37
	s_nop 1
	v_add_u32_e32 v196, s8, v135
	v_mad_i64_i32 v[196:197], s[8:9], v196, s70, v[136:137]
	global_load_dwordx4 v[196:199], v[196:197], off
.LBB0_1262:
	s_or_b64 exec, exec, s[12:13]
	v_mad_u32_u24 v207, v135, s33, v134
.LBB0_1263:
	s_or_b64 exec, exec, s[10:11]
	s_movk_i32 s8, 0xf0
	v_cmp_gt_i32_e32 vcc, s8, v164
	s_and_saveexec_b64 s[10:11], vcc
	s_cbranch_execz .LBB0_1267
	v_add_u32_e32 v200, 0x800, v164
	v_ashrrev_i32_e32 v135, 4, v200
	v_readlane_b32 s8, v253, 38
	v_mov_b32_e32 v200, 0
	v_mov_b32_e32 v201, 0
	v_cmp_lt_i32_e32 vcc, s8, v135
	v_mov_b32_e32 v202, 0
	v_mov_b32_e32 v203, 0
	s_and_saveexec_b64 s[12:13], vcc
	s_cbranch_execz .LBB0_1266
	v_readlane_b32 s8, v253, 37
	s_nop 1
	v_add_u32_e32 v200, s8, v135
	v_mad_i64_i32 v[200:201], s[8:9], v200, s70, v[136:137]
	global_load_dwordx4 v[200:203], v[200:201], off
.LBB0_1266:
	s_or_b64 exec, exec, s[12:13]
	v_mad_u32_u24 v208, v135, s33, v134
.LBB0_1267:
	s_or_b64 exec, exec, s[10:11]
	s_waitcnt vmcnt(0)
	s_movk_i32 s8, 0x8f0
	v_cmp_gt_i32_e32 vcc, s8, v164
	s_and_saveexec_b64 s[10:11], vcc
	ds_write_b128 v204, v[130:133]
	s_or_b64 exec, exec, s[10:11]
	s_movk_i32 s8, 0x6f0
	v_cmp_gt_i32_e32 vcc, s8, v164
	s_and_saveexec_b64 s[10:11], vcc
	ds_write_b128 v205, v[188:191]
	s_or_b64 exec, exec, s[10:11]
	s_movk_i32 s8, 0x4f0
	v_cmp_gt_i32_e32 vcc, s8, v164
	s_and_saveexec_b64 s[10:11], vcc
	ds_write_b128 v206, v[192:195]
	s_or_b64 exec, exec, s[10:11]
	s_movk_i32 s8, 0x2f0
	v_cmp_gt_i32_e32 vcc, s8, v164
	s_and_saveexec_b64 s[10:11], vcc
	ds_write_b128 v207, v[196:199]
	s_or_b64 exec, exec, s[10:11]
	s_movk_i32 s8, 0xf0
	v_cmp_gt_i32_e32 vcc, s8, v164
	s_and_saveexec_b64 s[10:11], vcc
	ds_write_b128 v208, v[200:203]
	s_or_b64 exec, exec, s[10:11]
	v_ashrrev_i32_e32 v168, 2, v164
	v_lshlrev_b32_e32 v130, 6, v164
	v_mul_lo_u32 v166, v168, s33
	v_and_b32_e32 v167, 0xc0, v130
	v_readlane_b32 s8, v254, 56
	v_mov_b32_e32 v130, 0
	v_mov_b32_e32 v131, v130
	v_add3_u32 v169, v166, v167, s8
	v_readlane_b32 s8, v253, 27
	v_mov_b32_e32 v160, v130
	v_mov_b32_e32 v161, v130
	v_mov_b32_e32 v158, v130
	v_mov_b32_e32 v159, v130
	v_mov_b32_e32 v156, v130
	v_mov_b32_e32 v157, v130
	v_mov_b32_e32 v154, v130
	v_mov_b32_e32 v155, v130
	v_mov_b32_e32 v152, v130
	v_mov_b32_e32 v153, v130
	v_mov_b32_e32 v150, v130
	v_mov_b32_e32 v151, v130
	v_mov_b32_e32 v148, v130
	v_mov_b32_e32 v149, v130
	v_mov_b32_e32 v146, v130
	v_mov_b32_e32 v147, v130
	v_mov_b32_e32 v144, v130
	v_mov_b32_e32 v145, v130
	v_mov_b32_e32 v142, v130
	v_mov_b32_e32 v143, v130
	v_mov_b32_e32 v140, v130
	v_mov_b32_e32 v141, v130
	v_mov_b32_e32 v138, v130
	v_mov_b32_e32 v139, v130
	v_mov_b32_e32 v136, v130
	v_mov_b32_e32 v137, v130
	v_mov_b32_e32 v134, v130
	v_mov_b32_e32 v135, v130
	v_mov_b32_e32 v132, v130
	v_mov_b32_e32 v133, v130
	s_waitcnt lgkmcnt(0)
	s_barrier
.LBB0_1268:
	ds_read_b128 v[170:173], v169
	ds_read_b128 v[174:177], v169 offset:16
	ds_read_b128 v[178:181], v169 offset:32
	ds_read_b128 v[182:185], v169 offset:48
	s_add_i32 s8, s8, -1
	s_waitcnt lgkmcnt(3)
	v_lshlrev_b32_e32 v186, 16, v170
	v_and_b32_e32 v187, 0xffff0000, v170
	v_lshlrev_b32_e32 v170, 16, v171
	v_and_b32_e32 v171, 0xffff0000, v171
	v_pk_add_f32 v[158:159], v[158:159], v[170:171]
	v_lshlrev_b32_e32 v170, 16, v172
	v_and_b32_e32 v171, 0xffff0000, v172
	v_pk_add_f32 v[156:157], v[156:157], v[170:171]
	v_lshlrev_b32_e32 v170, 16, v173
	v_and_b32_e32 v171, 0xffff0000, v173
	v_pk_add_f32 v[154:155], v[154:155], v[170:171]
	s_waitcnt lgkmcnt(2)
	v_lshlrev_b32_e32 v170, 16, v174
	v_and_b32_e32 v171, 0xffff0000, v174
	v_pk_add_f32 v[152:153], v[152:153], v[170:171]
	v_lshlrev_b32_e32 v170, 16, v175
	v_and_b32_e32 v171, 0xffff0000, v175
	v_pk_add_f32 v[150:151], v[150:151], v[170:171]
	v_lshlrev_b32_e32 v170, 16, v176
	v_and_b32_e32 v171, 0xffff0000, v176
	v_pk_add_f32 v[148:149], v[148:149], v[170:171]
	v_lshlrev_b32_e32 v170, 16, v177
	v_and_b32_e32 v171, 0xffff0000, v177
	v_pk_add_f32 v[146:147], v[146:147], v[170:171]
	s_waitcnt lgkmcnt(1)
	v_lshlrev_b32_e32 v170, 16, v178
	v_and_b32_e32 v171, 0xffff0000, v178
	v_pk_add_f32 v[144:145], v[144:145], v[170:171]
	v_lshlrev_b32_e32 v170, 16, v179
	v_and_b32_e32 v171, 0xffff0000, v179
	v_pk_add_f32 v[142:143], v[142:143], v[170:171]
	v_lshlrev_b32_e32 v170, 16, v180
	v_and_b32_e32 v171, 0xffff0000, v180
	v_pk_add_f32 v[140:141], v[140:141], v[170:171]
	v_lshlrev_b32_e32 v170, 16, v181
	v_and_b32_e32 v171, 0xffff0000, v181
	v_pk_add_f32 v[138:139], v[138:139], v[170:171]
	s_waitcnt lgkmcnt(0)
	v_lshlrev_b32_e32 v170, 16, v182
	v_and_b32_e32 v171, 0xffff0000, v182
	v_pk_add_f32 v[136:137], v[136:137], v[170:171]
	v_lshlrev_b32_e32 v170, 16, v183
	v_and_b32_e32 v171, 0xffff0000, v183
	v_pk_add_f32 v[134:135], v[134:135], v[170:171]
	v_lshlrev_b32_e32 v170, 16, v184
	v_and_b32_e32 v171, 0xffff0000, v184
	v_pk_add_f32 v[132:133], v[132:133], v[170:171]
	v_lshlrev_b32_e32 v170, 16, v185
	v_and_b32_e32 v171, 0xffff0000, v185
	v_pk_add_f32 v[160:161], v[160:161], v[186:187]
	v_pk_add_f32 v[130:131], v[130:131], v[170:171]
	v_add_u32_e32 v169, 0xfffffef0, v169
	s_cmp_lg_u32 s8, 0
	s_cbranch_scc1 .LBB0_1268
	v_readlane_b32 s8, v253, 39
	v_add3_u32 v182, 0, v166, v167
	s_mov_b64 s[10:11], 0x11101000
	v_add_u32_e32 v168, s8, v168
	v_readlane_b32 s8, v253, 27
	s_mov_b32 s72, 0
	s_nop 0
	v_min_i32_e32 v168, s8, v168
	v_cvt_f32_i32_e32 v170, v168
	ds_read_b128 v[166:169], v182 offset:4080
	v_div_scale_f32 v171, s[8:9], v170, v170, 1.0
	v_rcp_f32_e32 v172, v171
	v_div_scale_f32 v173, vcc, 1.0, v170, 1.0
	s_waitcnt lgkmcnt(0)
	v_lshlrev_b32_e32 v184, 16, v166
	v_fma_f32 v174, -v171, v172, 1.0
	v_fmac_f32_e32 v172, v174, v172
	v_mul_f32_e32 v174, v173, v172
	v_fma_f32 v175, -v171, v174, v173
	v_fmac_f32_e32 v174, v175, v172
	v_fma_f32 v171, -v171, v174, v173
	v_div_fmas_f32 v171, v171, v172, v174
	v_div_fixup_f32 v183, v171, v170, 1.0
	v_fma_f32 v160, v183, v160, -v184
	v_and_b32_e32 v166, 0xffff0000, v166
	v_fma_f32 v161, v183, v161, -v166
	v_cvt_pk_bf16_f32 v166, v160, v161
	v_lshlrev_b32_e32 v160, 16, v167
	v_fma_f32 v158, v183, v158, -v160
	v_and_b32_e32 v160, 0xffff0000, v167
	v_fma_f32 v159, v183, v159, -v160
	v_cvt_pk_bf16_f32 v167, v158, v159
	v_lshlrev_b32_e32 v158, 16, v168
	ds_read_b128 v[170:173], v182 offset:4096
	ds_read_b128 v[174:177], v182 offset:4112
	ds_read_b128 v[178:181], v182 offset:4128
	v_fma_f32 v156, v183, v156, -v158
	v_and_b32_e32 v158, 0xffff0000, v168
	v_fma_f32 v157, v183, v157, -v158
	v_cvt_pk_bf16_f32 v168, v156, v157
	v_lshlrev_b32_e32 v156, 16, v169
	v_fma_f32 v154, v183, v154, -v156
	v_and_b32_e32 v156, 0xffff0000, v169
	v_fma_f32 v155, v183, v155, -v156
	v_cvt_pk_bf16_f32 v169, v154, v155
	s_waitcnt lgkmcnt(2)
	v_lshlrev_b32_e32 v154, 16, v170
	v_fma_f32 v152, v183, v152, -v154
	v_and_b32_e32 v154, 0xffff0000, v170
	v_fma_f32 v153, v183, v153, -v154
	v_cvt_pk_bf16_f32 v152, v152, v153
	v_lshlrev_b32_e32 v153, 16, v171
	v_fma_f32 v150, v183, v150, -v153
	v_and_b32_e32 v153, 0xffff0000, v171
	v_fma_f32 v151, v183, v151, -v153
	v_cvt_pk_bf16_f32 v153, v150, v151
	v_lshlrev_b32_e32 v150, 16, v172
	v_fma_f32 v148, v183, v148, -v150
	v_and_b32_e32 v150, 0xffff0000, v172
	v_fma_f32 v149, v183, v149, -v150
	v_cvt_pk_bf16_f32 v154, v148, v149
	v_lshlrev_b32_e32 v148, 16, v173
	v_fma_f32 v146, v183, v146, -v148
	v_and_b32_e32 v148, 0xffff0000, v173
	v_fma_f32 v147, v183, v147, -v148
	v_cvt_pk_bf16_f32 v155, v146, v147
	s_waitcnt lgkmcnt(1)
	v_lshlrev_b32_e32 v146, 16, v174
	v_fma_f32 v144, v183, v144, -v146
	v_and_b32_e32 v146, 0xffff0000, v174
	v_fma_f32 v145, v183, v145, -v146
	v_cvt_pk_bf16_f32 v144, v144, v145
	v_lshlrev_b32_e32 v145, 16, v175
	v_fma_f32 v142, v183, v142, -v145
	v_and_b32_e32 v145, 0xffff0000, v175
	v_fma_f32 v143, v183, v143, -v145
	v_cvt_pk_bf16_f32 v145, v142, v143
	v_lshlrev_b32_e32 v142, 16, v176
	v_fma_f32 v140, v183, v140, -v142
	v_and_b32_e32 v142, 0xffff0000, v176
	v_fma_f32 v141, v183, v141, -v142
	v_cvt_pk_bf16_f32 v146, v140, v141
	v_lshlrev_b32_e32 v140, 16, v177
	v_fma_f32 v138, v183, v138, -v140
	v_and_b32_e32 v140, 0xffff0000, v177
	v_fma_f32 v139, v183, v139, -v140
	v_cvt_pk_bf16_f32 v147, v138, v139
	s_waitcnt lgkmcnt(0)
	v_lshlrev_b32_e32 v138, 16, v178
	v_fma_f32 v136, v183, v136, -v138
	v_and_b32_e32 v138, 0xffff0000, v178
	v_fma_f32 v137, v183, v137, -v138
	v_cvt_pk_bf16_f32 v136, v136, v137
	v_lshlrev_b32_e32 v137, 16, v179
	v_fma_f32 v134, v183, v134, -v137
	v_and_b32_e32 v137, 0xffff0000, v179
	v_fma_f32 v135, v183, v135, -v137
	v_cvt_pk_bf16_f32 v137, v134, v135
	v_lshlrev_b32_e32 v134, 16, v180
	v_fma_f32 v132, v183, v132, -v134
	v_and_b32_e32 v134, 0xffff0000, v180
	v_fma_f32 v133, v183, v133, -v134
	v_cvt_pk_bf16_f32 v138, v132, v133
	v_lshlrev_b32_e32 v132, 16, v181
	v_fma_f32 v130, v183, v130, -v132
	v_and_b32_e32 v132, 0xffff0000, v181
	s_ashr_i32 s8, s15, 2
	v_fma_f32 v131, v183, v131, -v132
	v_and_or_b32 v142, s8, -16, v165
	v_cvt_pk_bf16_f32 v139, v130, v131
	v_mul_lo_u32 v130, v142, s33
	v_and_b32_e32 v131, 48, v164
	v_add3_u32 v143, 0, v130, v131
	ds_write_b128 v182, v[166:169] offset:40960
	ds_write_b128 v182, v[152:155] offset:40976
	ds_write_b128 v182, v[144:147] offset:40992
	ds_write_b128 v182, v[136:139] offset:41008
	s_waitcnt lgkmcnt(0)
	s_barrier
	ds_read_b128 v[134:137], v143 offset:40960
	ds_read_b128 v[130:133], v143 offset:41024
	s_waitcnt vmcnt(31) lgkmcnt(1)
	v_mfma_f32_16x16x32_bf16 v[114:117], v[114:117], v[134:137], 0
	v_readlane_b32 s8, v253, 32
	s_waitcnt vmcnt(30) lgkmcnt(0)
	v_mfma_f32_16x16x32_bf16 v[138:141], v[110:113], v[130:133], v[114:117]
	s_nop 4
	ds_read_b128 v[114:117], v143 offset:41088
	ds_read_b128 v[110:113], v143 offset:41152
	s_waitcnt vmcnt(29) lgkmcnt(1)
	v_mfma_f32_16x16x32_bf16 v[106:109], v[106:109], v[114:117], v[138:141]
	s_waitcnt vmcnt(28) lgkmcnt(0)
	v_mfma_f32_16x16x32_bf16 v[102:105], v[102:105], v[110:113], v[106:109]
	s_waitcnt vmcnt(1)
	v_mfma_f32_16x16x32_bf16 v[106:109], v[126:129], v[134:137], 0
	v_add_u32_e32 v126, s8, v142
	v_mfma_f32_16x16x32_bf16 v[106:109], v[122:125], v[130:133], v[106:109]
	v_mov_b64_e32 v[122:123], s[24:25]
	v_mad_i64_i32 v[122:123], s[8:9], v126, s70, v[122:123]
	v_mfma_f32_16x16x32_bf16 v[106:109], v[118:121], v[114:117], v[106:109]
	v_readlane_b32 s8, v253, 29
	s_lshl_b32 s28, s8, 1
	v_lshl_add_u64 v[122:123], v[122:123], 0, s[28:29]
	v_mfma_f32_16x16x32_bf16 v[118:121], v[98:101], v[134:137], 0
	v_lshlrev_b32_e32 v124, 3, v163
	v_mov_b32_e32 v125, v33
	v_lshl_add_u64 v[100:101], v[122:123], 0, v[124:125]
	v_mfma_f32_16x16x32_bf16 v[94:97], v[94:97], v[130:133], v[118:121]
	s_mov_b32 s9, 0x11101000
	v_lshl_add_u64 v[98:99], v[100:101], 0, s[10:11]
	v_add_co_u32_e32 v100, vcc, s9, v100
	v_mfma_f32_16x16x32_bf16 v[90:93], v[90:93], v[114:117], v[94:97]
	s_lshl_b32 s8, s8, 2
	v_addc_co_u32_e32 v101, vcc, 0, v101, vcc
	v_mfma_f32_16x16x32_bf16 v[94:97], v[82:85], v[134:137], 0
	s_add_u32 s10, s2, s8
	global_load_dwordx2 v[118:119], v[98:99], off offset:32
	global_load_dwordx2 v[120:121], v[98:99], off offset:64
	global_load_dwordx2 v[122:123], v[98:99], off offset:96
	global_load_dwordx2 v[124:125], v[98:99], off offset:128
	global_load_dwordx2 v[84:85], v[100:101], off
	global_load_dwordx2 v[126:127], v[98:99], off offset:160
	global_load_dwordx2 v[128:129], v[98:99], off offset:192
	global_load_dwordx2 v[82:83], v[98:99], off offset:224
	v_mfma_f32_16x16x32_bf16 v[78:81], v[78:81], v[130:133], v[94:97]
	s_addc_u32 s11, s14, 0
	s_lshl_b32 s8, s18, 11
	v_mfma_f32_16x16x32_bf16 v[74:77], v[74:77], v[114:117], v[78:81]
	s_mov_b32 s2, 0
	s_waitcnt vmcnt(3)
	v_lshlrev_b32_e32 v94, 16, v84
	s_nop 1
	global_load_dwordx4 v[78:81], v32, s[10:11]
	global_load_dwordx4 v[188:191], v32, s[10:11] offset:64
	global_load_dwordx4 v[192:195], v32, s[10:11] offset:128
	global_load_dwordx4 v[196:199], v32, s[10:11] offset:192
	global_load_dwordx4 v[200:203], v32, s[10:11] offset:256
	global_load_dwordx4 v[210:213], v32, s[10:11] offset:320
	global_load_dwordx4 v[214:217], v32, s[10:11] offset:384
	global_load_dwordx4 v[228:231], v32, s[10:11] offset:448
	v_mfma_f32_16x16x32_bf16 v[70:73], v[70:73], v[134:137], 0
	s_waitcnt vmcnt(0)
	v_mul_f32_e32 v78, v102, v78
	v_mfma_f32_16x16x32_bf16 v[66:69], v[66:69], v[130:133], v[70:73]
	v_mul_f32_e32 v78, v78, v94
	v_mfma_f32_16x16x32_bf16 v[58:61], v[58:61], v[114:117], v[66:69]
	s_nop 2
	v_mul_f32_e32 v70, v103, v79
	v_and_b32_e32 v71, 0xffff0000, v84
	v_mul_f32_e32 v70, v70, v71
	v_mfma_f32_16x16x32_bf16 v[66:69], v[86:89], v[134:137], 0
	v_mul_f32_e32 v71, v104, v80
	v_lshlrev_b32_e32 v72, 16, v85
	v_mul_f32_e32 v71, v71, v72
	v_mfma_f32_16x16x32_bf16 v[62:65], v[62:65], v[130:133], v[66:69]
	v_mul_f32_e32 v72, v105, v81
	v_and_b32_e32 v73, 0xffff0000, v85
	v_cvt_pk_bf16_f32 v70, v78, v70
	v_mfma_f32_16x16x32_bf16 v[50:53], v[50:53], v[114:117], v[62:65]
	s_nop 0
	v_mul_f32_e32 v66, v72, v73
	v_cvt_pk_bf16_f32 v71, v71, v66
	global_store_dwordx2 v[100:101], v[70:71], off
	v_mfma_f32_16x16x32_bf16 v[38:41], v[38:41], v[110:113], v[106:109]
	s_nop 0
	v_mov_b64_e32 v[62:63], v[188:189]
	v_mov_b64_e32 v[64:65], v[190:191]
	v_lshlrev_b32_e32 v66, 16, v118
	v_and_b32_e32 v67, 0xffff0000, v118
	v_mfma_f32_16x16x32_bf16 v[54:57], v[54:57], v[134:137], 0
	v_mfma_f32_16x16x32_bf16 v[20:23], v[20:23], v[110:113], v[90:93]
	s_nop 0
	v_mul_f32_e32 v38, v38, v62
	v_mul_f32_e32 v39, v39, v63
	v_mul_f32_e32 v38, v38, v66
	v_mul_f32_e32 v40, v40, v64
	v_mul_f32_e32 v39, v39, v67
	v_cvt_pk_bf16_f32 v62, v38, v39
	v_lshlrev_b32_e32 v38, 16, v119
	v_mul_f32_e32 v63, v40, v38
	v_mul_f32_e32 v64, v41, v65
	v_mfma_f32_16x16x32_bf16 v[38:41], v[46:49], v[130:133], v[54:57]
	v_and_b32_e32 v65, 0xffff0000, v119
	v_mul_f32_e32 v46, v64, v65
	v_cvt_pk_bf16_f32 v63, v63, v46
	global_store_dwordx2 v[98:99], v[62:63], off offset:32
	v_mfma_f32_16x16x32_bf16 v[38:41], v[42:45], v[114:117], v[38:41]
	v_mov_b64_e32 v[42:43], v[192:193]
	v_mov_b64_e32 v[44:45], v[194:195]
	v_lshlrev_b32_e32 v46, 16, v120
	v_and_b32_e32 v47, 0xffff0000, v120
	v_lshlrev_b32_e32 v48, 16, v121
	v_and_b32_e32 v49, 0xffff0000, v121
	v_mfma_f32_16x16x32_bf16 v[16:19], v[16:19], v[110:113], v[74:77]
	v_mul_f32_e32 v20, v20, v42
	v_mul_f32_e32 v21, v21, v43
	v_mul_f32_e32 v22, v22, v44
	v_mul_f32_e32 v23, v23, v45
	v_mul_f32_e32 v20, v20, v46
	v_mul_f32_e32 v21, v21, v47
	v_mul_f32_e32 v22, v22, v48
	v_mul_f32_e32 v23, v23, v49
	v_cvt_pk_bf16_f32 v20, v20, v21
	v_cvt_pk_bf16_f32 v21, v22, v23
	global_store_dwordx2 v[98:99], v[20:21], off offset:64
	v_mov_b64_e32 v[20:21], v[196:197]
	v_mov_b64_e32 v[22:23], v[198:199]
	v_lshlrev_b32_e32 v42, 16, v122
	v_and_b32_e32 v43, 0xffff0000, v122
	v_lshlrev_b32_e32 v44, 16, v123
	v_and_b32_e32 v45, 0xffff0000, v123
	v_mfma_f32_16x16x32_bf16 v[8:11], v[8:11], v[134:137], 0
	v_mul_f32_e32 v16, v16, v20
	v_mul_f32_e32 v17, v17, v21
	v_mul_f32_e32 v18, v18, v22
	v_mul_f32_e32 v19, v19, v23
	v_mul_f32_e32 v16, v16, v42
	v_mul_f32_e32 v17, v17, v43
	v_mul_f32_e32 v18, v18, v44
	v_mul_f32_e32 v19, v19, v45
	v_cvt_pk_bf16_f32 v16, v16, v17
	v_cvt_pk_bf16_f32 v17, v18, v19
	global_store_dwordx2 v[98:99], v[16:17], off offset:96
	v_mov_b64_e32 v[16:17], v[200:201]
	v_mov_b64_e32 v[18:19], v[202:203]
	v_mfma_f32_16x16x32_bf16 v[20:23], v[34:37], v[110:113], v[58:61]
	v_lshlrev_b32_e32 v34, 16, v124
	v_and_b32_e32 v35, 0xffff0000, v124
	v_lshlrev_b32_e32 v36, 16, v125
	v_and_b32_e32 v37, 0xffff0000, v125
	v_mfma_f32_16x16x32_bf16 v[4:7], v[4:7], v[130:133], v[8:11]
	s_nop 1
	v_mul_f32_e32 v16, v20, v16
	v_mul_f32_e32 v17, v21, v17
	v_mul_f32_e32 v18, v22, v18
	v_mul_f32_e32 v19, v23, v19
	v_mul_f32_e32 v16, v16, v34
	v_mul_f32_e32 v17, v17, v35
	v_mul_f32_e32 v18, v18, v36
	v_mul_f32_e32 v19, v19, v37
	v_cvt_pk_bf16_f32 v16, v16, v17
	v_cvt_pk_bf16_f32 v17, v18, v19
	global_store_dwordx2 v[98:99], v[16:17], off offset:128
	v_mov_b64_e32 v[16:17], v[210:211]
	v_mov_b64_e32 v[18:19], v[212:213]
	v_mfma_f32_16x16x32_bf16 v[20:23], v[28:31], v[110:113], v[50:53]
	v_lshlrev_b32_e32 v28, 16, v126
	v_and_b32_e32 v29, 0xffff0000, v126
	v_lshlrev_b32_e32 v30, 16, v127
	v_and_b32_e32 v31, 0xffff0000, v127
	v_mfma_f32_16x16x32_bf16 v[0:3], v[0:3], v[114:117], v[4:7]
	s_nop 1
	v_mul_f32_e32 v16, v20, v16
	v_mul_f32_e32 v17, v21, v17
	v_mul_f32_e32 v18, v22, v18
	v_mul_f32_e32 v19, v23, v19
	v_mul_f32_e32 v16, v16, v28
	v_mul_f32_e32 v17, v17, v29
	v_mul_f32_e32 v18, v18, v30
	v_mul_f32_e32 v19, v19, v31
	v_cvt_pk_bf16_f32 v16, v16, v17
	v_cvt_pk_bf16_f32 v17, v18, v19
	global_store_dwordx2 v[98:99], v[16:17], off offset:160
	v_mov_b64_e32 v[16:17], v[214:215]
	v_mov_b64_e32 v[18:19], v[216:217]
	v_mfma_f32_16x16x32_bf16 v[20:23], v[24:27], v[110:113], v[38:41]
	v_lshlrev_b32_e32 v24, 16, v128
	v_and_b32_e32 v25, 0xffff0000, v128
	v_lshlrev_b32_e32 v26, 16, v129
	v_and_b32_e32 v27, 0xffff0000, v129
	v_mfma_f32_16x16x32_bf16 v[0:3], v[12:15], v[110:113], v[0:3]
	v_lshlrev_b32_e32 v4, 16, v82
	v_and_b32_e32 v5, 0xffff0000, v82
	v_lshlrev_b32_e32 v6, 16, v83
	v_and_b32_e32 v7, 0xffff0000, v83
	v_mul_f32_e32 v16, v20, v16
	v_mul_f32_e32 v17, v21, v17
	v_mul_f32_e32 v18, v22, v18
	v_mul_f32_e32 v19, v23, v19
	v_mul_f32_e32 v16, v16, v24
	v_mul_f32_e32 v17, v17, v25
	v_mul_f32_e32 v18, v18, v26
	v_mul_f32_e32 v19, v19, v27
	v_cvt_pk_bf16_f32 v16, v16, v17
	v_cvt_pk_bf16_f32 v17, v18, v19
	global_store_dwordx2 v[98:99], v[16:17], off offset:192
	v_mov_b64_e32 v[16:17], v[228:229]
	v_mov_b64_e32 v[18:19], v[230:231]
	v_xor_b32_e32 v20, 16, v226
	v_xor_b32_e32 v21, 32, v226
	v_cmp_lt_i32_e32 vcc, v20, v162
	v_readlane_b32 s10, v251, 33
	v_readlane_b32 s11, v251, 34
	v_cndmask_b32_e32 v20, v226, v20, vcc
	v_cmp_lt_i32_e32 vcc, v21, v162
	s_add_u32 s66, s10, s8
	v_lshlrev_b32_e32 v100, 2, v20
	v_cndmask_b32_e32 v8, v226, v21, vcc
	v_lshlrev_b32_e32 v101, 2, v8
	s_addc_u32 s67, s11, 0
	v_mul_f32_e32 v0, v0, v16
	v_mul_f32_e32 v1, v1, v17
	v_mul_f32_e32 v2, v2, v18
	v_mul_f32_e32 v3, v3, v19
	v_mul_f32_e32 v0, v0, v4
	v_mul_f32_e32 v1, v1, v5
	v_mul_f32_e32 v2, v2, v6
	v_mul_f32_e32 v3, v3, v7
	v_cvt_pk_bf16_f32 v0, v0, v1
	v_cvt_pk_bf16_f32 v1, v2, v3
	global_store_dwordx2 v[98:99], v[0:1], off offset:224
	s_barrier
	s_mov_b32 s48, 0
	s_branch .Lpf_issue
